# v52 plus an early L2 write-back issued by the first workgroup of each XCD to reach a grid barrier
# speedup vs baseline: 1.0015x; 1.0015x over previous
.Lxb_g2_wait:
	v_mul_lo_u32 v12, v6, v4
	v_cmp_ne_u32_e32 vcc, v12, v2
	s_cbranch_vccnz .Lxb_g2_w2
	buffer_wbl2 sc1
